# v27 + prologue weight prep: 8 weight and 8 gain loads issued together per trip with one wait, instead of a vmcnt(0) round trip per row
# speedup vs baseline: 1.0027x; 1.0007x over previous
; #define LAS __attribute__((address_space(3)))
; __device__ __forceinline__ void wprep_item(const float* __restrict__ W, int K, int N, const float* __restrict__ gain, bf16_t* __restrict__ WT, int mat, LAS float* scr, int item, int lane) {
;     const int nblk = N / 32, kb = item / nblk, nb = item % nblk, k0 = 64 * kb, n0 = 32 * nb;
; #pragma unroll 8
;     for (int i = 0; i < 32; ++i) { const int kk = 2 * i + (lane >> 5); const float g = gain ? gain[k0 + kk] : 1.0f; scr[kk * 33 + (lane & 31)] = W[(size_t)(k0 + kk) * N + n0 + (lane & 31)] * g; }
.LBB0_440:
	v_lshl_add_u64 v[44:45], v[26:27], 0, v[6:7]
	global_load_dword v48, v[44:45], off
	v_lshl_add_u64 v[46:47], v[22:23], 0, v[6:7]
	global_load_dword v49, v[46:47], off
	v_lshl_add_u64 v[44:45], v[20:21], 0, v[6:7]
	global_load_dword v50, v[44:45], off
	v_lshl_add_u64 v[46:47], v[18:19], 0, v[6:7]
	global_load_dword v51, v[46:47], off
	v_lshl_add_u64 v[44:45], v[16:17], 0, v[6:7]
	global_load_dword v52, v[44:45], off
	v_lshl_add_u64 v[46:47], v[14:15], 0, v[6:7]
	global_load_dword v53, v[46:47], off
	v_lshl_add_u64 v[44:45], v[12:13], 0, v[6:7]
	global_load_dword v54, v[44:45], off
	v_lshl_add_u64 v[46:47], v[8:9], 0, v[6:7]
	global_load_dword v55, v[46:47], off
	s_andn2_b64 vcc, exec, s[36:37]
	s_cbranch_vccnz .Lwp_nogain
	v_lshl_add_u64 v[44:45], v[24:25], 0, s[4:5]
	global_load_dword v56, v[44:45], off
	v_lshl_add_u64 v[46:47], v[10:11], 0, s[4:5]
	global_load_dword v57, v[46:47], off offset:8
	global_load_dword v58, v[46:47], off offset:16
	global_load_dword v59, v[46:47], off offset:24
	global_load_dword v60, v[46:47], off offset:32
	global_load_dword v61, v[46:47], off offset:40
	global_load_dword v62, v[46:47], off offset:48
	global_load_dword v63, v[46:47], off offset:56
	s_branch .Lwp_go
.Lwp_nogain:
	v_mov_b32_e32 v56, 1.0
	v_mov_b32_e32 v57, 1.0
	v_mov_b32_e32 v58, 1.0
	v_mov_b32_e32 v59, 1.0
	v_mov_b32_e32 v60, 1.0
	v_mov_b32_e32 v61, 1.0
	v_mov_b32_e32 v62, 1.0
	v_mov_b32_e32 v63, 1.0
.Lwp_go:
	s_add_u32 s4, s4, 64
	s_addc_u32 s5, s5, 0
	v_lshl_add_u64 v[26:27], v[26:27], 0, s[18:19]
	v_lshl_add_u64 v[22:23], v[22:23], 0, s[18:19]
	v_lshl_add_u64 v[20:21], v[20:21], 0, s[18:19]
	v_lshl_add_u64 v[18:19], v[18:19], 0, s[18:19]
	v_lshl_add_u64 v[16:17], v[16:17], 0, s[18:19]
	v_lshl_add_u64 v[14:15], v[14:15], 0, s[18:19]
	v_lshl_add_u64 v[12:13], v[12:13], 0, s[18:19]
	v_lshl_add_u64 v[8:9], v[8:9], 0, s[18:19]
	s_cmpk_eq_i32 s4, 0x100
	s_waitcnt vmcnt(0)
	v_mul_f32_e32 v48, v56, v48
	v_mul_f32_e32 v49, v57, v49
	v_mul_f32_e32 v50, v58, v50
	v_mul_f32_e32 v51, v59, v51
	v_mul_f32_e32 v52, v60, v52
	v_mul_f32_e32 v53, v61, v53
	v_mul_f32_e32 v54, v62, v54
	v_mul_f32_e32 v55, v63, v55
	ds_write_b32 v42, v48
	ds_write_b32 v42, v49 offset:264
	ds_write_b32 v42, v50 offset:528
	ds_write_b32 v42, v51 offset:792
	ds_write_b32 v42, v52 offset:1056
	ds_write_b32 v42, v53 offset:1320
	ds_write_b32 v42, v54 offset:1584
	ds_write_b32 v42, v55 offset:1848
	v_add_u32_e32 v42, 0x840, v42
	s_cbranch_scc0 .LBB0_440
